# baseline (speedup 1.0000x reference)
;     ...
;         for (int it = TIDX; it < 2 * (DFF / 8); it += 512) {
;           const int row = it / (DFF / 8), ck = it - row * (DFF / 8);
;           const int ch = ck * 8;
;           const int pg = (ch >> 7) * 256 + (ch & 127);
;           float res[8];
; #pragma unroll
;           for (int h = 0; h < 2; ++h) {
;             float cur[8], p1[8], p2[8], w0[8], w1[8], w2[8], bb[8];
;             const int pc = pg + h * 128, oc = ch + h * DFF;
;             ld8(UPB + ((size_t)pm * 4 + row) * UPW + pc, cur);
;             if (row == 1) { ld8(UPB + ((size_t)pm * 4 + 0) * UPW + pc, p1); ld8(UPB + ((size_t)(pm - 1) * 4 + 3) * UPW + pc, p2); }
;             else          { ld8(UPB + ((size_t)(pm - 1) * 4 + 3) * UPW + pc, p1); ld8(UPB + ((size_t)(pm - 1) * 4 + 2) * UPW + pc, p2); }
;             ld8f(p->w_conv + oc, w0); ld8f(p->w_conv + UPW + oc, w1); ld8f(p->w_conv + 2 * UPW + oc, w2); ld8f(p->b_conv + oc, bb);
.LBB0_543:
	v_mul_hi_i32 v2, v1, s40
	v_lshrrev_b32_e32 v3, 31, v2
	v_ashrrev_i32_e32 v2, 6, v2
	v_add_u32_e32 v8, v2, v3
	v_mad_i32_i24 v2, v8, s41, v1
	v_lshlrev_b32_e32 v6, 3, v2
	v_ashrrev_i32_e32 v9, 31, v8
	v_lshlrev_b32_e32 v2, 4, v2
	v_and_b32_e32 v3, 0x78, v6
	v_lshl_add_u64 v[4:5], s[18:19], 0, v[8:9]
	v_mov_b64_e32 v[12:13], s[12:13]
	v_and_or_b32 v2, v2, s43, v3
	v_mad_u64_u32 v[12:13], s[2:3], v4, s61, v[12:13]
	v_add_u32_e32 v3, 0xfffffea0, v1
	v_cmp_gt_u32_e64 s[2:3], s44, v3
	v_ashrrev_i32_e32 v3, 31, v2
	v_mad_i32_i24 v13, v5, s61, v13
	v_lshlrev_b64 v[14:15], 1, v[2:3]
	v_lshl_add_u64 v[16:17], v[12:13], 0, v[14:15]
	global_load_dwordx4 v[2:5], v[16:17], off
	global_load_dwordx4 v[152:155], v[16:17], off offset:256
	v_mov_b32_e32 v140, s28
	v_mov_b32_e32 v141, s35
	v_cndmask_b32_e64 v141, v140, v141, s[2:3]
	v_mov_b32_e32 v140, s26
	v_mov_b32_e32 v142, s29
	v_cndmask_b32_e64 v140, v140, v142, s[2:3]
	v_lshl_add_u64 v[164:165], v[140:141], 0, v[14:15]
	global_load_dwordx4 v[144:147], v[164:165], off
	global_load_dwordx4 v[156:159], v[164:165], off offset:256
	v_cndmask_b32_e64 v142, v203, v204, s[2:3]
	v_mov_b32_e32 v143, v0
	v_lshl_add_u64 v[166:167], s[36:37], 0, v[142:143]
	v_lshl_add_u64 v[166:167], v[166:167], 0, v[14:15]
	global_load_dwordx4 v[148:151], v[166:167], off
	global_load_dwordx4 v[160:163], v[166:167], off offset:256
	v_cndmask_b32_e64 v12, v203, v204, s[2:3]
	v_mov_b32_e32 v13, v0
	v_ashrrev_i32_e32 v7, 31, v6
	v_add_u32_e32 v8, s25, v8
	s_waitcnt vmcnt(0)
	v_lshlrev_b32_e32 v40, 16, v2
	v_and_b32_e32 v41, 0xffff0000, v2
	v_lshlrev_b32_e32 v72, 16, v3
	v_and_b32_e32 v73, 0xffff0000, v3
	v_mov_b32_e32 v2, s28
	v_mov_b32_e32 v3, s35
	v_lshlrev_b32_e32 v74, 16, v4
	v_and_b32_e32 v75, 0xffff0000, v4
	v_cndmask_b32_e64 v3, v2, v3, s[2:3]
	v_mov_b32_e32 v2, s26
	v_mov_b32_e32 v4, s29
	v_cndmask_b32_e64 v2, v2, v4, s[2:3]
	v_lshl_add_u64 v[18:19], v[2:3], 0, v[14:15]
	v_lshlrev_b32_e32 v76, 16, v5
	v_and_b32_e32 v77, 0xffff0000, v5
	v_mov_b32_e32 v2, v144
	v_mov_b32_e32 v3, v145
	v_mov_b32_e32 v4, v146
	v_mov_b32_e32 v5, v147
	s_waitcnt vmcnt(0)
	v_and_b32_e32 v79, 0xffff0000, v5
	v_lshlrev_b32_e32 v78, 16, v5
	v_and_b32_e32 v81, 0xffff0000, v4
	v_lshlrev_b32_e32 v80, 16, v4
	v_lshl_add_u64 v[4:5], s[36:37], 0, v[12:13]
	v_lshl_add_u64 v[20:21], v[4:5], 0, v[14:15]
	v_lshlrev_b64 v[4:5], 2, v[6:7]
	v_and_b32_e32 v83, 0xffff0000, v3
	v_lshlrev_b32_e32 v82, 16, v3
	v_and_b32_e32 v43, 0xffff0000, v2
	v_mov_b32_e32 v12, v148
	v_mov_b32_e32 v13, v149
	v_mov_b32_e32 v14, v150
	v_mov_b32_e32 v15, v151
	v_lshl_add_u64 v[48:49], s[4:5], 0, v[4:5]
	v_lshl_add_u64 v[56:57], s[20:21], 0, v[4:5]
	v_lshl_add_u64 v[64:65], s[22:23], 0, v[4:5]
	v_lshl_add_u64 v[46:47], s[6:7], 0, v[4:5]
	v_lshlrev_b32_e32 v42, 16, v2
	v_mov_b32_e32 v2, v152
	v_mov_b32_e32 v3, v153
	v_mov_b32_e32 v4, v154
	v_mov_b32_e32 v5, v155
	v_lshl_add_u64 v[50:51], v[46:47], 0, s[88:89]
	v_lshl_add_u64 v[52:53], v[48:49], 0, s[88:89]
	v_lshl_add_u64 v[60:61], v[56:57], 0, s[88:89]
	v_lshl_add_u64 v[68:69], v[64:65], 0, s[88:89]
	s_waitcnt vmcnt(1)
	v_and_b32_e32 v85, 0xffff0000, v15
	v_lshlrev_b32_e32 v84, 16, v15
	v_and_b32_e32 v87, 0xffff0000, v14
	v_lshlrev_b32_e32 v86, 16, v14
	v_and_b32_e32 v89, 0xffff0000, v13
	v_lshlrev_b32_e32 v88, 16, v13
	v_and_b32_e32 v45, 0xffff0000, v12
	v_lshlrev_b32_e32 v44, 16, v12
	s_waitcnt vmcnt(0)
	v_lshlrev_b32_e32 v90, 16, v2
	v_and_b32_e32 v91, 0xffff0000, v2
	v_lshlrev_b32_e32 v92, 16, v3
	v_and_b32_e32 v93, 0xffff0000, v3
	v_lshlrev_b32_e32 v94, 16, v4
	v_and_b32_e32 v95, 0xffff0000, v4
	v_lshlrev_b32_e32 v96, 16, v5
	v_and_b32_e32 v97, 0xffff0000, v5
	v_mov_b32_e32 v2, v156
	v_mov_b32_e32 v3, v157
	v_mov_b32_e32 v4, v158
	v_mov_b32_e32 v5, v159
	v_mov_b32_e32 v12, v160
	v_mov_b32_e32 v13, v161
	v_mov_b32_e32 v14, v162
	v_mov_b32_e32 v15, v163
	s_waitcnt vmcnt(1)
	v_and_b32_e32 v99, 0xffff0000, v5
	v_lshlrev_b32_e32 v98, 16, v5
	v_and_b32_e32 v101, 0xffff0000, v4
	v_lshlrev_b32_e32 v100, 16, v4
	v_and_b32_e32 v103, 0xffff0000, v3
	v_lshlrev_b32_e32 v102, 16, v3
	v_and_b32_e32 v105, 0xffff0000, v2
	s_waitcnt vmcnt(0)
	v_and_b32_e32 v107, 0xffff0000, v15
	v_lshlrev_b32_e32 v106, 16, v15
	v_and_b32_e32 v109, 0xffff0000, v14
	v_lshlrev_b32_e32 v108, 16, v14
	v_and_b32_e32 v111, 0xffff0000, v13
	v_lshlrev_b32_e32 v110, 16, v13
	v_and_b32_e32 v113, 0xffff0000, v12
	v_lshlrev_b32_e32 v112, 16, v12
	v_lshlrev_b32_e32 v104, 16, v2
	global_load_dwordx4 v[2:5], v[46:47], off offset:16
	global_load_dwordx4 v[12:15], v[46:47], off
	global_load_dwordx4 v[16:19], v[48:49], off offset:16
	global_load_dwordx4 v[20:23], v[48:49], off
	global_load_dwordx4 v[24:27], v[56:57], off offset:16
	global_load_dwordx4 v[28:31], v[56:57], off
	global_load_dwordx4 v[32:35], v[64:65], off offset:16
	global_load_dwordx4 v[36:39], v[64:65], off
	s_waitcnt vmcnt(5)
; #define GAS __attribute__((address_space(1)))
;     ...
;             ld8f(p->w_conv + oc, w0); ld8f(p->w_conv + UPW + oc, w1); ld8f(p->w_conv + 2 * UPW + oc, w2); ld8f(p->b_conv + oc, bb);
; #pragma unroll
;             for (int k = 0; k < 8; ++k) {
;               float cv = bb[k] + w0[k] * p2[k] + w1[k] * p1[k] + w2[k] * cur[k];
;               if (h == 0) res[k] = gelu_f(cv); else res[k] *= cv;
;             }
;           }
;           *(GAS uint4*)(FI + (size_t)(brow + row) * DFF + ch) =
;               make_uint4(pack2(res[0], res[1]), pack2(res[2], res[3]), pack2(res[4], res[5]), pack2(res[6], res[7]));
;         }
	v_pk_fma_f32 v[2:3], v[16:17], v[86:87], v[2:3]
	s_waitcnt vmcnt(4)
	v_pk_fma_f32 v[12:13], v[20:21], v[44:45], v[12:13]
	v_pk_fma_f32 v[14:15], v[22:23], v[88:89], v[14:15]
	s_waitcnt vmcnt(2)
	v_pk_fma_f32 v[12:13], v[28:29], v[42:43], v[12:13]
	v_pk_fma_f32 v[14:15], v[30:31], v[82:83], v[14:15]
	s_waitcnt vmcnt(0)
	v_pk_fma_f32 v[12:13], v[36:37], v[40:41], v[12:13]
	v_pk_fma_f32 v[14:15], v[38:39], v[72:73], v[14:15]
	v_pk_mul_f32 v[20:21], v[12:13], v[12:13]
	v_pk_fma_f32 v[2:3], v[24:25], v[80:81], v[2:3]
	v_fmamk_f32 v9, v20, 0xbdd2d3e7, v198
	v_mul_f32_e32 v9, v12, v9
	v_exp_f32_e32 v9, v9
	v_pk_fma_f32 v[2:3], v[32:33], v[74:75], v[2:3]
	v_add_f32_e32 v9, 1.0, v9
	v_rcp_f32_e32 v20, v9
	v_fmamk_f32 v9, v21, 0xbdd2d3e7, v198
	v_mul_f32_e32 v9, v13, v9
	v_exp_f32_e32 v9, v9
	v_pk_mul_f32 v[16:17], v[2:3], v[2:3]
	v_add_f32_e32 v9, 1.0, v9
	v_rcp_f32_e32 v21, v9
	s_nop 0
	v_pk_mul_f32 v[12:13], v[12:13], v[20:21]
	v_add_co_u32_e64 v20, s[2:3], s80, v46
	s_nop 1
	v_addc_co_u32_e64 v21, s[2:3], 0, v47, s[2:3]
	global_load_dwordx4 v[40:43], v[20:21], off offset:3072
	global_load_dwordx4 v[44:47], v[50:51], off offset:16
	v_add_co_u32_e64 v20, s[2:3], s80, v48
	s_nop 1
	v_addc_co_u32_e64 v21, s[2:3], 0, v49, s[2:3]
	global_load_dwordx4 v[48:51], v[20:21], off offset:3072
	s_nop 0
	global_load_dwordx4 v[52:55], v[52:53], off offset:16
	v_add_co_u32_e64 v20, s[2:3], s80, v56
	s_nop 1
	v_addc_co_u32_e64 v21, s[2:3], 0, v57, s[2:3]
	global_load_dwordx4 v[56:59], v[20:21], off offset:3072
	s_nop 0
	global_load_dwordx4 v[60:63], v[60:61], off offset:16
	v_add_co_u32_e64 v20, s[2:3], s80, v64
	s_nop 1
	v_addc_co_u32_e64 v21, s[2:3], 0, v65, s[2:3]
	global_load_dwordx4 v[64:67], v[20:21], off offset:3072
	s_nop 0
	global_load_dwordx4 v[68:71], v[68:69], off offset:16
	s_waitcnt vmcnt(5)
	v_pk_fma_f32 v[20:21], v[48:49], v[112:113], v[40:41]
	s_waitcnt vmcnt(3)
	v_pk_fma_f32 v[20:21], v[56:57], v[104:105], v[20:21]
	s_waitcnt vmcnt(1)
	v_pk_fma_f32 v[20:21], v[64:65], v[90:91], v[20:21]
	s_nop 0
	v_pk_mul_f32 v[12:13], v[12:13], v[20:21]
	v_pk_mul_f32 v[20:21], v[14:15], v[14:15]
	s_nop 0
	v_fmamk_f32 v9, v20, 0xbdd2d3e7, v198
	v_mul_f32_e32 v9, v14, v9
	v_exp_f32_e32 v9, v9
	s_nop 0
	v_add_f32_e32 v9, 1.0, v9
	v_rcp_f32_e32 v20, v9
	v_fmamk_f32 v9, v21, 0xbdd2d3e7, v198
	v_mul_f32_e32 v9, v15, v9
	v_exp_f32_e32 v9, v9
	s_nop 0
	v_add_f32_e32 v9, 1.0, v9
	v_rcp_f32_e32 v21, v9
	v_fmamk_f32 v9, v16, 0xbdd2d3e7, v198
	v_mul_f32_e32 v9, v2, v9
	v_exp_f32_e32 v9, v9
	v_pk_mul_f32 v[14:15], v[14:15], v[20:21]
	v_pk_fma_f32 v[20:21], v[50:51], v[110:111], v[42:43]
	v_add_f32_e32 v9, 1.0, v9
	v_rcp_f32_e32 v16, v9
	v_fmamk_f32 v9, v17, 0xbdd2d3e7, v198
	v_mul_f32_e32 v9, v3, v9
	v_exp_f32_e32 v9, v9
	v_pk_fma_f32 v[20:21], v[58:59], v[102:103], v[20:21]
	v_add_f32_e32 v9, 1.0, v9
	v_rcp_f32_e32 v17, v9
	v_pk_fma_f32 v[20:21], v[66:67], v[92:93], v[20:21]
	v_pk_mul_f32 v[2:3], v[2:3], v[16:17]
	v_pk_fma_f32 v[16:17], v[52:53], v[108:109], v[44:45]
	v_pk_mul_f32 v[14:15], v[14:15], v[20:21]
	v_pk_fma_f32 v[16:17], v[60:61], v[100:101], v[16:17]
	s_waitcnt vmcnt(0)
	v_pk_fma_f32 v[16:17], v[68:69], v[94:95], v[16:17]
	s_nop 0
	v_pk_mul_f32 v[16:17], v[2:3], v[16:17]
	v_pk_fma_f32 v[2:3], v[18:19], v[84:85], v[4:5]
	s_nop 0
	v_pk_fma_f32 v[2:3], v[26:27], v[78:79], v[2:3]
	s_nop 0
	v_pk_fma_f32 v[2:3], v[34:35], v[76:77], v[2:3]
	s_nop 0
	v_pk_mul_f32 v[4:5], v[2:3], v[2:3]
	s_nop 0
	v_fmamk_f32 v4, v4, 0xbdd2d3e7, v198
	v_fmamk_f32 v5, v5, 0xbdd2d3e7, v198
	v_mul_f32_e32 v4, v2, v4
	v_mul_f32_e32 v5, v3, v5
	v_exp_f32_e32 v4, v4
	v_exp_f32_e32 v5, v5
	v_add_f32_e32 v4, 1.0, v4
	v_add_f32_e32 v5, 1.0, v5
	v_rcp_f32_e32 v4, v4
	v_rcp_f32_e32 v5, v5
	s_nop 0
	v_pk_mul_f32 v[2:3], v[2:3], v[4:5]
	v_pk_fma_f32 v[4:5], v[54:55], v[106:107], v[46:47]
	s_nop 0
	v_pk_fma_f32 v[4:5], v[62:63], v[98:99], v[4:5]
	s_nop 0
	v_pk_fma_f32 v[4:5], v[70:71], v[96:97], v[4:5]
	s_nop 0
	v_pk_mul_f32 v[18:19], v[2:3], v[4:5]
	v_cvt_pk_bf16_f32 v2, v12, v13
	v_mov_b64_e32 v[12:13], s[14:15]
	v_mad_i64_i32 v[8:9], s[2:3], v8, s63, v[12:13]
	v_cmp_lt_i32_e64 s[2:3], s45, v1
	v_cvt_pk_bf16_f32 v3, v14, v15
	v_cvt_pk_bf16_f32 v4, v16, v17
	v_cvt_pk_bf16_f32 v5, v18, v19
	v_lshl_add_u64 v[6:7], v[6:7], 1, v[8:9]
	v_add_u32_e32 v1, 0x200, v1
	s_or_b64 s[38:39], s[2:3], s[38:39]
	global_store_dwordx4 v[6:7], v[2:5], off
	s_andn2_b64 exec, exec, s[38:39]
	s_cbranch_execnz .LBB0_543
	s_branch .LBB0_536

;     ...
;         for (int it = TIDX; it < 2 * (DFF / 8); it += 512) {
;           const int row = it / (DFF / 8), ck = it - row * (DFF / 8);
;           const int ch = ck * 8;
;           const int pg = (ch >> 7) * 256 + (ch & 127);
;           float res[8];
; #pragma unroll
;           for (int h = 0; h < 2; ++h) {
;             float cur[8], p1[8], p2[8], w0[8], w1[8], w2[8], bb[8];
;             const int pc = pg + h * 128, oc = ch + h * DFF;
;             ld8(UPB + ((size_t)pm * 4 + row) * UPW + pc, cur);
;             if (row == 1) { ld8(UPB + ((size_t)pm * 4 + 0) * UPW + pc, p1); ld8(UPB + ((size_t)(pm - 1) * 4 + 3) * UPW + pc, p2); }
;             else          { ld8(UPB + ((size_t)(pm - 1) * 4 + 3) * UPW + pc, p1); ld8(UPB + ((size_t)(pm - 1) * 4 + 2) * UPW + pc, p2); }
;             ld8f(p->w_conv + oc, w0); ld8f(p->w_conv + UPW + oc, w1); ld8f(p->w_conv + 2 * UPW + oc, w2); ld8f(p->b_conv + oc, bb);
.LBB0_927:
	v_mul_hi_i32 v2, v1, s42
	v_lshrrev_b32_e32 v3, 31, v2
	v_ashrrev_i32_e32 v2, 6, v2
	v_add_u32_e32 v8, v2, v3
	v_mad_i32_i24 v2, v8, s44, v1
	v_lshlrev_b32_e32 v6, 3, v2
	v_ashrrev_i32_e32 v9, 31, v8
	v_lshlrev_b32_e32 v2, 4, v2
	v_and_b32_e32 v3, 0x78, v6
	v_lshl_add_u64 v[4:5], s[18:19], 0, v[8:9]
	v_mov_b64_e32 v[12:13], s[12:13]
	v_and_or_b32 v2, v2, s45, v3
	v_mad_u64_u32 v[12:13], s[2:3], v4, s61, v[12:13]
	v_add_u32_e32 v3, 0xfffffea0, v1
	v_cmp_gt_u32_e64 s[2:3], s48, v3
	v_ashrrev_i32_e32 v3, 31, v2
	v_mad_i32_i24 v13, v5, s61, v13
	v_lshlrev_b64 v[14:15], 1, v[2:3]
	v_lshl_add_u64 v[16:17], v[12:13], 0, v[14:15]
	global_load_dwordx4 v[2:5], v[16:17], off
	global_load_dwordx4 v[152:155], v[16:17], off offset:256
	v_mov_b32_e32 v140, s28
	v_mov_b32_e32 v141, s38
	v_cndmask_b32_e64 v141, v140, v141, s[2:3]
	v_mov_b32_e32 v140, s27
	v_mov_b32_e32 v142, s29
	v_cndmask_b32_e64 v140, v140, v142, s[2:3]
	v_lshl_add_u64 v[164:165], v[140:141], 0, v[14:15]
	global_load_dwordx4 v[144:147], v[164:165], off
	global_load_dwordx4 v[156:159], v[164:165], off offset:256
	v_cndmask_b32_e64 v142, v203, v204, s[2:3]
	v_mov_b32_e32 v143, v0
	v_lshl_add_u64 v[166:167], s[36:37], 0, v[142:143]
	v_lshl_add_u64 v[166:167], v[166:167], 0, v[14:15]
	global_load_dwordx4 v[148:151], v[166:167], off
	global_load_dwordx4 v[160:163], v[166:167], off offset:256
	v_cndmask_b32_e64 v12, v203, v204, s[2:3]
	v_mov_b32_e32 v13, v0
	v_ashrrev_i32_e32 v7, 31, v6
	v_add_u32_e32 v8, s26, v8
	s_waitcnt vmcnt(0)
	v_lshlrev_b32_e32 v40, 16, v2
	v_and_b32_e32 v41, 0xffff0000, v2
	v_lshlrev_b32_e32 v72, 16, v3
	v_and_b32_e32 v73, 0xffff0000, v3
	v_mov_b32_e32 v2, s28
	v_mov_b32_e32 v3, s38
	v_lshlrev_b32_e32 v74, 16, v4
	v_and_b32_e32 v75, 0xffff0000, v4
	v_cndmask_b32_e64 v3, v2, v3, s[2:3]
	v_mov_b32_e32 v2, s27
	v_mov_b32_e32 v4, s29
	v_cndmask_b32_e64 v2, v2, v4, s[2:3]
	v_lshl_add_u64 v[18:19], v[2:3], 0, v[14:15]
	v_lshlrev_b32_e32 v76, 16, v5
	v_and_b32_e32 v77, 0xffff0000, v5
	v_mov_b32_e32 v2, v144
	v_mov_b32_e32 v3, v145
	v_mov_b32_e32 v4, v146
	v_mov_b32_e32 v5, v147
	s_waitcnt vmcnt(0)
	v_and_b32_e32 v79, 0xffff0000, v5
	v_lshlrev_b32_e32 v78, 16, v5
	v_and_b32_e32 v81, 0xffff0000, v4
	v_lshlrev_b32_e32 v80, 16, v4
	v_lshl_add_u64 v[4:5], s[36:37], 0, v[12:13]
	v_lshl_add_u64 v[20:21], v[4:5], 0, v[14:15]
	v_lshlrev_b64 v[4:5], 2, v[6:7]
	v_and_b32_e32 v83, 0xffff0000, v3
	v_lshlrev_b32_e32 v82, 16, v3
	v_and_b32_e32 v43, 0xffff0000, v2
	v_mov_b32_e32 v12, v148
	v_mov_b32_e32 v13, v149
	v_mov_b32_e32 v14, v150
	v_mov_b32_e32 v15, v151
	v_lshl_add_u64 v[48:49], s[4:5], 0, v[4:5]
	v_lshl_add_u64 v[56:57], s[20:21], 0, v[4:5]
	v_lshl_add_u64 v[64:65], s[22:23], 0, v[4:5]
	v_lshl_add_u64 v[46:47], s[6:7], 0, v[4:5]
	v_lshlrev_b32_e32 v42, 16, v2
	v_mov_b32_e32 v2, v152
	v_mov_b32_e32 v3, v153
	v_mov_b32_e32 v4, v154
	v_mov_b32_e32 v5, v155
	v_lshl_add_u64 v[50:51], v[46:47], 0, s[88:89]
	v_lshl_add_u64 v[52:53], v[48:49], 0, s[88:89]
	v_lshl_add_u64 v[60:61], v[56:57], 0, s[88:89]
	v_lshl_add_u64 v[68:69], v[64:65], 0, s[88:89]
	s_waitcnt vmcnt(1)
	v_and_b32_e32 v85, 0xffff0000, v15
	v_lshlrev_b32_e32 v84, 16, v15
	v_and_b32_e32 v87, 0xffff0000, v14
	v_lshlrev_b32_e32 v86, 16, v14
	v_and_b32_e32 v89, 0xffff0000, v13
	v_lshlrev_b32_e32 v88, 16, v13
	v_and_b32_e32 v45, 0xffff0000, v12
	v_lshlrev_b32_e32 v44, 16, v12
	s_waitcnt vmcnt(0)
	v_lshlrev_b32_e32 v90, 16, v2
	v_and_b32_e32 v91, 0xffff0000, v2
	v_lshlrev_b32_e32 v92, 16, v3
	v_and_b32_e32 v93, 0xffff0000, v3
	v_lshlrev_b32_e32 v94, 16, v4
	v_and_b32_e32 v95, 0xffff0000, v4
	v_lshlrev_b32_e32 v96, 16, v5
	v_and_b32_e32 v97, 0xffff0000, v5
	v_mov_b32_e32 v2, v156
	v_mov_b32_e32 v3, v157
	v_mov_b32_e32 v4, v158
	v_mov_b32_e32 v5, v159
	v_mov_b32_e32 v12, v160
	v_mov_b32_e32 v13, v161
	v_mov_b32_e32 v14, v162
	v_mov_b32_e32 v15, v163
	s_waitcnt vmcnt(1)
	v_and_b32_e32 v99, 0xffff0000, v5
	v_lshlrev_b32_e32 v98, 16, v5
	v_and_b32_e32 v101, 0xffff0000, v4
	v_lshlrev_b32_e32 v100, 16, v4
	v_and_b32_e32 v103, 0xffff0000, v3
	v_lshlrev_b32_e32 v102, 16, v3
	v_and_b32_e32 v105, 0xffff0000, v2
	s_waitcnt vmcnt(0)
	v_and_b32_e32 v107, 0xffff0000, v15
	v_lshlrev_b32_e32 v106, 16, v15
	v_and_b32_e32 v109, 0xffff0000, v14
	v_lshlrev_b32_e32 v108, 16, v14
	v_and_b32_e32 v111, 0xffff0000, v13
	v_lshlrev_b32_e32 v110, 16, v13
	v_and_b32_e32 v113, 0xffff0000, v12
	v_lshlrev_b32_e32 v112, 16, v12
	v_lshlrev_b32_e32 v104, 16, v2
	global_load_dwordx4 v[2:5], v[46:47], off offset:16
	global_load_dwordx4 v[12:15], v[46:47], off
	global_load_dwordx4 v[16:19], v[48:49], off offset:16
	global_load_dwordx4 v[20:23], v[48:49], off
	global_load_dwordx4 v[24:27], v[56:57], off offset:16
	global_load_dwordx4 v[28:31], v[56:57], off
	global_load_dwordx4 v[32:35], v[64:65], off offset:16
	global_load_dwordx4 v[36:39], v[64:65], off
	s_waitcnt vmcnt(5)
; #define GAS __attribute__((address_space(1)))
;     ...
;             ld8f(p->w_conv + oc, w0); ld8f(p->w_conv + UPW + oc, w1); ld8f(p->w_conv + 2 * UPW + oc, w2); ld8f(p->b_conv + oc, bb);
; #pragma unroll
;             for (int k = 0; k < 8; ++k) {
;               float cv = bb[k] + w0[k] * p2[k] + w1[k] * p1[k] + w2[k] * cur[k];
;               if (h == 0) res[k] = gelu_f(cv); else res[k] *= cv;
;             }
;           }
;           *(GAS uint4*)(FI + (size_t)(brow + row) * DFF + ch) =
;               make_uint4(pack2(res[0], res[1]), pack2(res[2], res[3]), pack2(res[4], res[5]), pack2(res[6], res[7]));
;         }
	v_pk_fma_f32 v[2:3], v[16:17], v[86:87], v[2:3]
	s_waitcnt vmcnt(4)
	v_pk_fma_f32 v[12:13], v[20:21], v[44:45], v[12:13]
	v_pk_fma_f32 v[14:15], v[22:23], v[88:89], v[14:15]
	s_waitcnt vmcnt(2)
	v_pk_fma_f32 v[12:13], v[28:29], v[42:43], v[12:13]
	v_pk_fma_f32 v[14:15], v[30:31], v[82:83], v[14:15]
	s_waitcnt vmcnt(0)
	v_pk_fma_f32 v[12:13], v[36:37], v[40:41], v[12:13]
	v_pk_fma_f32 v[14:15], v[38:39], v[72:73], v[14:15]
	v_pk_mul_f32 v[20:21], v[12:13], v[12:13]
	v_pk_fma_f32 v[2:3], v[24:25], v[80:81], v[2:3]
	v_fmamk_f32 v9, v20, 0xbdd2d3e7, v198
	v_mul_f32_e32 v9, v12, v9
	v_exp_f32_e32 v9, v9
	v_pk_fma_f32 v[2:3], v[32:33], v[74:75], v[2:3]
	v_add_f32_e32 v9, 1.0, v9
	v_rcp_f32_e32 v20, v9
	v_fmamk_f32 v9, v21, 0xbdd2d3e7, v198
	v_mul_f32_e32 v9, v13, v9
	v_exp_f32_e32 v9, v9
	v_pk_mul_f32 v[16:17], v[2:3], v[2:3]
	v_add_f32_e32 v9, 1.0, v9
	v_rcp_f32_e32 v21, v9
	s_nop 0
	v_pk_mul_f32 v[12:13], v[12:13], v[20:21]
	v_add_co_u32_e64 v20, s[2:3], s80, v46
	s_nop 1
	v_addc_co_u32_e64 v21, s[2:3], 0, v47, s[2:3]
	global_load_dwordx4 v[40:43], v[20:21], off offset:3072
	global_load_dwordx4 v[44:47], v[50:51], off offset:16
	v_add_co_u32_e64 v20, s[2:3], s80, v48
	s_nop 1
	v_addc_co_u32_e64 v21, s[2:3], 0, v49, s[2:3]
	global_load_dwordx4 v[48:51], v[20:21], off offset:3072
	s_nop 0
	global_load_dwordx4 v[52:55], v[52:53], off offset:16
	v_add_co_u32_e64 v20, s[2:3], s80, v56
	s_nop 1
	v_addc_co_u32_e64 v21, s[2:3], 0, v57, s[2:3]
	global_load_dwordx4 v[56:59], v[20:21], off offset:3072
	s_nop 0
	global_load_dwordx4 v[60:63], v[60:61], off offset:16
	v_add_co_u32_e64 v20, s[2:3], s80, v64
	s_nop 1
	v_addc_co_u32_e64 v21, s[2:3], 0, v65, s[2:3]
	global_load_dwordx4 v[64:67], v[20:21], off offset:3072
	s_nop 0
	global_load_dwordx4 v[68:71], v[68:69], off offset:16
	s_waitcnt vmcnt(5)
	v_pk_fma_f32 v[20:21], v[48:49], v[112:113], v[40:41]
	s_waitcnt vmcnt(3)
	v_pk_fma_f32 v[20:21], v[56:57], v[104:105], v[20:21]
	s_waitcnt vmcnt(1)
	v_pk_fma_f32 v[20:21], v[64:65], v[90:91], v[20:21]
	s_nop 0
	v_pk_mul_f32 v[12:13], v[12:13], v[20:21]
	v_pk_mul_f32 v[20:21], v[14:15], v[14:15]
	s_nop 0
	v_fmamk_f32 v9, v20, 0xbdd2d3e7, v198
	v_mul_f32_e32 v9, v14, v9
	v_exp_f32_e32 v9, v9
	s_nop 0
	v_add_f32_e32 v9, 1.0, v9
	v_rcp_f32_e32 v20, v9
	v_fmamk_f32 v9, v21, 0xbdd2d3e7, v198
	v_mul_f32_e32 v9, v15, v9
	v_exp_f32_e32 v9, v9
	s_nop 0
	v_add_f32_e32 v9, 1.0, v9
	v_rcp_f32_e32 v21, v9
	v_fmamk_f32 v9, v16, 0xbdd2d3e7, v198
	v_mul_f32_e32 v9, v2, v9
	v_exp_f32_e32 v9, v9
	v_pk_mul_f32 v[14:15], v[14:15], v[20:21]
	v_pk_fma_f32 v[20:21], v[50:51], v[110:111], v[42:43]
	v_add_f32_e32 v9, 1.0, v9
	v_rcp_f32_e32 v16, v9
	v_fmamk_f32 v9, v17, 0xbdd2d3e7, v198
	v_mul_f32_e32 v9, v3, v9
	v_exp_f32_e32 v9, v9
	v_pk_fma_f32 v[20:21], v[58:59], v[102:103], v[20:21]
	v_add_f32_e32 v9, 1.0, v9
	v_rcp_f32_e32 v17, v9
	v_pk_fma_f32 v[20:21], v[66:67], v[92:93], v[20:21]
	v_pk_mul_f32 v[2:3], v[2:3], v[16:17]
	v_pk_fma_f32 v[16:17], v[52:53], v[108:109], v[44:45]
	v_pk_mul_f32 v[14:15], v[14:15], v[20:21]
	v_pk_fma_f32 v[16:17], v[60:61], v[100:101], v[16:17]
	s_waitcnt vmcnt(0)
	v_pk_fma_f32 v[16:17], v[68:69], v[94:95], v[16:17]
	s_nop 0
	v_pk_mul_f32 v[16:17], v[2:3], v[16:17]
	v_pk_fma_f32 v[2:3], v[18:19], v[84:85], v[4:5]
	s_nop 0
	v_pk_fma_f32 v[2:3], v[26:27], v[78:79], v[2:3]
	s_nop 0
	v_pk_fma_f32 v[2:3], v[34:35], v[76:77], v[2:3]
	s_nop 0
	v_pk_mul_f32 v[4:5], v[2:3], v[2:3]
	s_nop 0
	v_fmamk_f32 v4, v4, 0xbdd2d3e7, v198
	v_fmamk_f32 v5, v5, 0xbdd2d3e7, v198
	v_mul_f32_e32 v4, v2, v4
	v_mul_f32_e32 v5, v3, v5
	v_exp_f32_e32 v4, v4
	v_exp_f32_e32 v5, v5
	v_add_f32_e32 v4, 1.0, v4
	v_add_f32_e32 v5, 1.0, v5
	v_rcp_f32_e32 v4, v4
	v_rcp_f32_e32 v5, v5
	s_nop 0
	v_pk_mul_f32 v[2:3], v[2:3], v[4:5]
	v_pk_fma_f32 v[4:5], v[54:55], v[106:107], v[46:47]
	s_nop 0
	v_pk_fma_f32 v[4:5], v[62:63], v[98:99], v[4:5]
	s_nop 0
	v_pk_fma_f32 v[4:5], v[70:71], v[96:97], v[4:5]
	s_nop 0
	v_pk_mul_f32 v[18:19], v[2:3], v[4:5]
	v_cvt_pk_bf16_f32 v2, v12, v13
	v_mov_b64_e32 v[12:13], s[14:15]
	v_mad_i64_i32 v[8:9], s[2:3], v8, s63, v[12:13]
	v_cmp_lt_i32_e64 s[2:3], s49, v1
	v_cvt_pk_bf16_f32 v3, v14, v15
	v_cvt_pk_bf16_f32 v4, v16, v17
	v_cvt_pk_bf16_f32 v5, v18, v19
	v_lshl_add_u64 v[6:7], v[6:7], 1, v[8:9]
	v_add_u32_e32 v1, 0x200, v1
	s_or_b64 s[40:41], s[2:3], s[40:41]
	global_store_dwordx4 v[6:7], v[2:5], off
	s_andn2_b64 exec, exec, s[40:41]
	s_cbranch_execnz .LBB0_927
	s_branch .LBB0_920
